# mLSTM step: the four state-weight vectors for the V^T scaling issued together behind the V^T reads (counted lgkmcnt) instead of three dependent LDS round trips
# speedup vs baseline: 1.0038x; 1.0029x over previous
.LBB0_1693:
	v_ashrrev_i32_e32 v99, 3, v80
	v_lshlrev_b32_e32 v0, 4, v8
	v_and_b32_e32 v84, 0x70, v0
	v_mul_lo_u32 v0, v99, s69
	s_waitcnt lgkmcnt(0)
	s_barrier
	v_lshl_add_u32 v0, v84, 1, v0
	ds_read_b128 v[10:13], v0 offset:54272
	ds_read_b128 v[32:35], v0 offset:54288
	v_lshlrev_b32_e32 v5, 2, v84
	v_or_b32_e32 v6, 0x21400, v5
	ds_read_b128 v[118:121], v6
	ds_read_b128 v[122:125], v6 offset:16
	ds_read_b128 v[200:203], v6 offset:32
	ds_read_b128 v[204:207], v6 offset:48
	v_add_u32_e32 v7, 0x11800, v0
	s_waitcnt lgkmcnt(5)
	v_lshlrev_b32_e32 v0, 16, v10
	v_and_b32_e32 v9, 0xffff0000, v10
	v_or_b32_e32 v10, 0x21410, v5
	v_lshlrev_b32_e32 v14, 16, v11
	v_and_b32_e32 v15, 0xffff0000, v11
	v_lshlrev_b32_e32 v40, 16, v12
	v_and_b32_e32 v41, 0xffff0000, v12
	ds_read_b64 v[82:83], v90
	v_lshlrev_b32_e32 v6, 16, v13
	v_and_b32_e32 v42, 0xffff0000, v13
	s_cmp_gt_u32 s77, 1
	s_waitcnt lgkmcnt(4)
	v_mul_f32_e32 v0, v118, v0
	v_mul_f32_e32 v9, v119, v9
	v_mul_f32_e32 v14, v120, v14
	s_waitcnt lgkmcnt(3)
	v_mul_f32_e32 v36, v122, v40
	v_mul_f32_e32 v13, v125, v42
	v_cvt_pk_bf16_f32 v10, v0, v9
	v_mul_f32_e32 v15, v121, v15
	v_mul_f32_e32 v37, v123, v41
	v_mul_f32_e32 v6, v124, v6
	v_cvt_pk_bf16_f32 v11, v14, v15
	v_cvt_pk_bf16_f32 v12, v36, v37
	v_cvt_pk_bf16_f32 v13, v6, v13
	ds_write_b128 v7, v[10:13]
	v_or_b32_e32 v10, 0x21420, v5
	v_or_b32_e32 v5, 0x21430, v5
	v_lshlrev_b32_e32 v0, 16, v32
	v_and_b32_e32 v6, 0xffff0000, v32
	v_lshlrev_b32_e32 v9, 16, v33
	v_and_b32_e32 v14, 0xffff0000, v33
	v_lshlrev_b32_e32 v15, 16, v34
	v_and_b32_e32 v36, 0xffff0000, v34
	v_lshlrev_b32_e32 v37, 16, v35
	v_and_b32_e32 v38, 0xffff0000, v35
	s_cselect_b64 s[54:55], -1, 0
	s_cmp_lt_u32 s77, 2
	v_ashrrev_i32_e32 v100, 5, v8
	v_and_b32_e32 v101, 31, v8
	s_waitcnt lgkmcnt(3)
	v_mul_f32_e32 v5, v201, v6
	v_mul_f32_e32 v6, v202, v9
	v_mul_f32_e32 v9, v203, v14
	s_waitcnt lgkmcnt(2)
	v_mul_f32_e32 v12, v204, v15
	v_mul_f32_e32 v13, v205, v36
	v_mul_f32_e32 v0, v200, v0
	v_mul_f32_e32 v14, v206, v37
	v_mul_f32_e32 v15, v207, v38
	v_cvt_pk_bf16_f32 v10, v0, v5
	v_cvt_pk_bf16_f32 v11, v6, v9
	v_cvt_pk_bf16_f32 v12, v12, v13
	v_cvt_pk_bf16_f32 v13, v14, v15
	ds_write_b128 v7, v[10:13] offset:16
	s_cbranch_scc1 .LBB0_1723
	ds_read_b128 v[10:13], v4
	v_lshlrev_b32_e32 v0, 2, v3
	v_or_b32_e32 v3, 0x21600, v0
	ds_read_b128 v[32:35], v3
	ds_read_b128 v[4:7], v4 offset:16
	s_waitcnt lgkmcnt(2)
	v_lshlrev_b32_e32 v9, 16, v10
	v_and_b32_e32 v14, 0xffff0000, v10
	v_add_u32_e32 v10, 0x21610, v0
	v_lshlrev_b32_e32 v15, 16, v11
	v_and_b32_e32 v36, 0xffff0000, v11
	v_lshlrev_b32_e32 v37, 16, v12
	v_and_b32_e32 v38, 0xffff0000, v12
	v_lshlrev_b32_e32 v3, 16, v13
	v_and_b32_e32 v39, 0xffff0000, v13
	ds_read_b128 v[10:13], v10
	s_waitcnt lgkmcnt(2)
	v_mul_f32_e32 v14, v33, v14
	v_fmac_f32_e32 v14, v32, v9
	v_fmac_f32_e32 v14, v34, v15
	v_fmac_f32_e32 v14, v35, v36
	s_waitcnt lgkmcnt(0)
	v_fmac_f32_e32 v14, v10, v37
	v_fmac_f32_e32 v14, v11, v38
	v_fmac_f32_e32 v14, v12, v3
	v_fmac_f32_e32 v14, v13, v39
	v_add_f32_e32 v3, 0, v14
	v_lshlrev_b32_e32 v9, 16, v4
	v_and_b32_e32 v14, 0xffff0000, v4
	v_add_u32_e32 v4, 0x21620, v0
	ds_read_b128 v[10:13], v4
	v_add_u32_e32 v0, 0x21630, v0
	v_lshlrev_b32_e32 v15, 16, v5
	v_and_b32_e32 v32, 0xffff0000, v5
	v_lshlrev_b32_e32 v33, 16, v6
	v_and_b32_e32 v34, 0xffff0000, v6
	v_lshlrev_b32_e32 v35, 16, v7
	v_and_b32_e32 v36, 0xffff0000, v7
	ds_read_b128 v[4:7], v0
	s_waitcnt lgkmcnt(1)
	v_mul_f32_e32 v0, v11, v14
	v_fmac_f32_e32 v0, v10, v9
	v_fmac_f32_e32 v0, v12, v15
	v_fmac_f32_e32 v0, v13, v32
	s_waitcnt lgkmcnt(0)
	v_fmac_f32_e32 v0, v4, v33
	v_fmac_f32_e32 v0, v5, v34
	v_fmac_f32_e32 v0, v6, v35
	v_fmac_f32_e32 v0, v7, v36
	v_and_b32_e32 v4, 64, v91
	v_add_f32_e32 v0, v3, v0
	v_xor_b32_e32 v3, 1, v91
	v_add_u32_e32 v9, 64, v4
	v_cmp_lt_i32_e32 vcc, v3, v9
	s_nop 1
	v_cndmask_b32_e32 v3, v91, v3, vcc
	v_lshlrev_b32_e32 v3, 2, v3
	ds_bpermute_b32 v3, v3, v0
	s_waitcnt lgkmcnt(0)
	v_add_f32_e32 v0, v0, v3
	v_xor_b32_e32 v3, 2, v91
	v_cmp_lt_i32_e32 vcc, v3, v9
	s_nop 1
	v_cndmask_b32_e32 v3, v91, v3, vcc
	v_lshlrev_b32_e32 v3, 2, v3
	ds_bpermute_b32 v3, v3, v0
	v_cmp_eq_u32_e32 vcc, 0, v85
	s_and_saveexec_b64 s[10:11], vcc
	s_cbranch_execz .LBB0_1696
	s_waitcnt lgkmcnt(0)
	v_add_f32_e32 v0, v0, v3
	v_lshl_add_u32 v2, v2, 2, v92
	ds_write_b32 v2, v0
